# grid barrier relaxed polling: s_sleep 6 between polls (less poll traffic on the counter line while stragglers finish)
# baseline (speedup 1.0000x reference)
.Lxb_spin:
	global_load_dword v5, v145, s[4:5] sc1
	s_add_i32 s36, s36, 1
	s_waitcnt vmcnt(0)
	v_cmp_lt_u32_e32 vcc, v5, v4
	s_cbranch_vccz .Lxb_done
	s_sleep 6
	s_cmp_lt_u32 s36, 0x40000
	s_cbranch_scc1 .Lxb_spin
